# tile order of the wide GEMM phases (P2/P8/P4) grouped 4 row tiles x 8 column tiles per XCD instead of 2 x 16 (L2 operand reuse)
# baseline (speedup 1.0000x reference)
;     __host__ __device__ bool next(int i, Unit& u) const { if (!b.next(i >> 1, u)) return false; u.sel = i & 1; return true; }
; #define PG8_STAGE(bufoff, gbase, voff) do { _Pragma("unroll") for (int _i = 0; _i < 2; ++_i) \
;         __builtin_amdgcn_global_load_lds((const unsigned*)((const char*)(gbase) + (voff)[_i]), (PG8_LAS unsigned*)(lds + (bufoff) + ldsw + _i * 8192), 16, 0, 0); } while (0)
; #define PG8_WAIT_V(n) asm volatile("s_waitcnt vmcnt(" #n ")" ::: "memory")
; #define PG8_BAR __builtin_amdgcn_s_barrier()
;     __host__ __device__ bool next(int i, Unit& u) const {
;         const long L = (long)i * G + c; if (L >= nwg) return false;
;         int wgid = (int)L; { const int q = nwg / NXCD, r = nwg % NXCD, xcd = wgid % NXCD, off = wgid / NXCD; wgid = (xcd < r ? xcd * (q + 1) : r * (q + 1) + (xcd - r) * q) + off; }
;         const int nig = WGM * nN, gid = wgid / nig, fm = gid * WGM, gsz = (nM - fm) < WGM ? (nM - fm) : WGM;
;         u.pm = fm + ((wgid % nig) % gsz); u.pn = (wgid % nig) / gsz; u.sel = 0; return true;
; template <class Epi, class Sched, bool ALIGN_EPI = false, bool SP2 = false>
; __device__ __forceinline__ void gemm_phase(PG8_LAS unsigned char* lds, const Gemm g, const Sched& S, const Epi& E) {
;     ...
;     const char* cA = PG8_ABASE(cur); const char* cB = PG8_BBASE(cur);
;     S.a_ready(cur);
;     if constexpr (SP2) {
;         PG8_STAGE(PG8_SB(0, 0), cB, voffB); PG8_STAGE(PG8_SB(0, 1), cB + hstep, voffB); PG8_STAGE(PG8_SA(0, 0), cA, voffA); PG8_STAGE(PG8_SA(0, 1), cA + hstep, voffA);
;         if (wr == 1) PG8_BAR;
;         PG8_WAIT_V(2); PG8_BAR;
;         PG8_STAGE(PG8_SB(1, 0), cB + kstep, voffB); PG8_STAGE(PG8_SA(1, 0), cA + kstepA, voffA); PG8_STAGE(PG8_SB(1, 1), cB + hstep + kstep, voffB);
;         PG8_WAIT_V(6); PG8_BAR;
.LBB0_198:
	s_cmp_lt_i32 s48, 3
	s_cselect_b64 s[2:3], -1, 0
	s_and_b64 s[2:3], s[2:3], s[0:1]
	s_andn2_b64 vcc, exec, s[2:3]
	v_writelane_b32 v254, s48, 8
	s_nop 1
	v_writelane_b32 v254, s49, 9
	s_cbranch_vccnz .LBB0_215
	v_readfirstlane_b32 s1, v0
	s_mov_b32 s0, 0
	s_cmpk_gt_i32 s87, 0xaff
	s_cbranch_scc1 .LBB0_215
	v_lshrrev_b32_e32 v1, 5, v0
	v_lshrrev_b32_e32 v3, 1, v0
	v_and_b32_e32 v1, 4, v1
	v_bfe_u32 v2, v0, 2, 2
	v_and_b32_e32 v3, 24, v3
	s_add_u32 s28, s78, 0x4000000
	v_or3_b32 v1, v1, v2, v3
	v_lshlrev_b32_e32 v2, 4, v0
	s_addc_u32 s29, s79, 0
	v_or_b32_e32 v10, 0x2000, v2
	s_add_u32 s30, s78, 0x900000
	v_lshrrev_b32_e32 v3, 7, v10
	s_movk_i32 s0, 0x60
	s_addc_u32 s31, s79, 0
	v_and_or_b32 v4, v3, s0, v1
	v_bfe_u32 v13, v0, 2, 4
	s_movk_i32 s0, 0x70
	s_ashr_i32 s35, s87, 31
	v_and_or_b32 v3, v3, s0, v13
	s_lshr_b32 s0, s35, 29
	s_add_i32 s0, s87, s0
	s_lshr_b32 s9, s1, 6
	s_waitcnt lgkmcnt(0)
	s_ashr_i32 s4, s0, 3
	s_and_b32 s0, s0, -8
	s_lshr_b32 s8, s1, 8
	s_lshl_b32 s34, s9, 10
	s_sub_i32 s0, s87, s0
	s_cmp_lt_i32 s0, 0
	s_movk_i32 s36, 0x161
	s_cselect_b32 s5, s36, 0x160
	s_mul_i32 s0, s0, s5
	s_add_i32 s0, s0, s4
	s_mul_hi_i32 s4, s0, 0x2e8ba2e9
	s_lshr_b32 s5, s4, 31
	s_ashr_i32 s4, s4, 4
	s_add_i32 s4, s4, s5
	s_lshl_b32 s5, s4, 2
	s_mul_i32 s4, s4, 88
	s_sub_i32 s4, s0, s4
	s_lshr_b32 s0, s4, 2
	s_and_b32 s4, s4, 3
	v_and_b32_e32 v5, 32, v0
	s_add_i32 s20, s5, s4
	v_bitop3_b32 v11, v2, v5, 48 bitop3:0x6c
	v_and_b32_e32 v12, 64, v0
	s_ashr_i32 s21, s20, 31
	s_bfe_i64 s[6:7], s[0:1], 0x100000
	v_or_b32_e32 v2, v11, v12
	s_lshl_b64 s[4:5], s[20:21], 19
	s_lshl_b64 s[6:7], s[6:7], 19
	v_lshl_or_b32 v132, v3, 11, v2
	v_lshrrev_b32_e32 v3, 3, v0
	s_add_u32 s24, s30, s6
	v_and_or_b32 v1, v3, 32, v1
	s_addc_u32 s25, s31, s7
	s_add_i32 s37, s34, 0
	v_lshl_or_b32 v134, v1, 11, v2
	s_add_i32 m0, s37, 0x10000
	v_lshl_or_b32 v130, v4, 11, v2
	global_load_lds_dwordx4 v134, s[24:25]
	s_add_i32 m0, s37, 0x12000
	s_add_u32 s6, s24, 0x40000
	global_load_lds_dwordx4 v130, s[24:25]
	s_addc_u32 s7, s25, 0
	s_add_i32 m0, s37, 0x14000
	v_and_or_b32 v1, v3, 48, v13
	global_load_lds_dwordx4 v134, s[6:7]
	s_add_i32 m0, s37, 0x16000
	s_add_u32 s22, s28, s4
	s_addc_u32 s23, s29, s5
	s_add_i32 s38, s37, 0x2000
	v_lshl_or_b32 v136, v1, 11, v2
	global_load_lds_dwordx4 v130, s[6:7]
	s_mov_b32 m0, s37
	s_add_u32 s4, s22, 0x40000
	global_load_lds_dwordx4 v136, s[22:23]
	s_mov_b32 m0, s38
	s_addc_u32 s5, s23, 0
	s_add_i32 s39, s37, 0x4000
	global_load_lds_dwordx4 v132, s[22:23]
	s_mov_b32 m0, s39
	s_add_i32 s40, s37, 0x6000
	global_load_lds_dwordx4 v136, s[4:5]
	s_mov_b32 m0, s40
	v_mov_b32_e32 v139, 0
	global_load_lds_dwordx4 v132, s[4:5]
	v_mov_b32_e32 v135, v139
	v_mov_b32_e32 v131, v139
	v_mov_b32_e32 v137, v139
	v_mov_b32_e32 v133, v139
	s_cmp_eq_u32 s8, 1
	v_lshl_add_u64 v[8:9], s[24:25], 0, v[134:135]
	v_lshl_add_u64 v[6:7], s[24:25], 0, v[130:131]
	v_lshl_add_u64 v[2:3], s[22:23], 0, v[136:137]
	s_cselect_b64 s[4:5], -1, 0
	s_cmp_lg_u32 s8, 1
	v_lshl_add_u64 v[4:5], s[22:23], 0, v[132:133]
	s_cbranch_scc1 .LBB0_202
	s_barrier

;     __host__ __device__ bool next(int i, Unit& u) const { if (!b.next(i >> 1, u)) return false; u.sel = i & 1; return true; }
; #define PG8_STAGE(bufoff, gbase, voff) do { _Pragma("unroll") for (int _i = 0; _i < 2; ++_i) \
;         __builtin_amdgcn_global_load_lds((const unsigned*)((const char*)(gbase) + (voff)[_i]), (PG8_LAS unsigned*)(lds + (bufoff) + ldsw + _i * 8192), 16, 0, 0); } while (0)
; #define PG8_LDA(dst, b, h) do { _Pragma("unroll") for (int m = 0; m < 4; ++m) _Pragma("unroll") for (int k = 0; k < 2; ++k) dst[m][k] = *(const PG8_LAS bf16x8*)(lds + PG8_SA(b, h) + aoff + m * 2048 + k * 1024); } while (0)
;     __host__ __device__ bool next(int i, Unit& u) const {
;         const long L = (long)i * G + c; if (L >= nwg) return false;
;         int wgid = (int)L; { const int q = nwg / NXCD, r = nwg % NXCD, xcd = wgid % NXCD, off = wgid / NXCD; wgid = (xcd < r ? xcd * (q + 1) : r * (q + 1) + (xcd - r) * q) + off; }
;         const int nig = WGM * nN, gid = wgid / nig, fm = gid * WGM, gsz = (nM - fm) < WGM ? (nM - fm) : WGM;
;         u.pm = fm + ((wgid % nig) % gsz); u.pn = (wgid % nig) / gsz; u.sel = 0; return true;
; template <class Epi, class Sched, bool ALIGN_EPI = false, bool SP2 = false>
; __device__ __forceinline__ void gemm_phase(PG8_LAS unsigned char* lds, const Gemm g, const Sched& S, const Epi& E) {
;     ...
;         for (int t = 0; t < nt; t += 2) {
;             const bool last = (t == nt - 2);
;             const char* a1 = cA + (size_t)(t + 1) * kstepA;
;             const char* a2 = last ? nA : cA + (size_t)(t + 2) * kstepA; const char* b2 = last ? nB : cB + (size_t)(t + 2) * kstep;
;             const char* a3 = a2 + kstepA; const char* b3 = b2 + kstep;
;             if (last && has_next) S.a_ready(nxt);
;             if constexpr (SP2) {
;             PG8_LDB(B0, 0, 0); PG8_LDB(B1, 0, 1); PG8_SCHED; PG8_LDA(At, 0, 0); PG8_STAGE(PG8_SA(1, 1), a1 + hstep, voffA);
;             PG8_WAIT_V(8); PG8_WAIT_L(0); PG8_BAR; PG8_MMA(0, 0, At, B0); PG8_MMA(0, 1, At, B1); PG8_BAR; PG8_SCHED;
;             if constexpr (Epi::PREFETCH) { if (t == tpf) E.prefetch(cur, wid, lane); }
;             PG8_LDA(At, 0, 1); PG8_STAGE(PG8_SB(0, 0), b2, voffB); PG8_STAGE(PG8_SB(0, 1), b2 + hstep, voffB); PG8_STAGE(PG8_SA(0, 0), a2, voffA);
;             PG8_WAIT_V(8); PG8_WAIT_L(0); PG8_BAR; PG8_MMA(1, 0, At, B0); PG8_MMA(1, 1, At, B1); PG8_BAR; PG8_SCHED;
.LBB0_205:
	s_add_u32 s22, s22, 0x40080
	s_addc_u32 s23, s23, 0
	s_add_u32 s52, s24, 0x100
	s_addc_u32 s53, s25, 0
	s_mov_b32 s54, -2
	ds_read_b128 v[154:157], v150
	ds_read_b128 v[158:161], v150 offset:1024
	ds_read_b128 v[162:165], v150 offset:2048
	ds_read_b128 v[166:169], v150 offset:3072
	ds_read_b128 v[170:173], v151
	ds_read_b128 v[174:177], v151 offset:1024
	ds_read_b128 v[178:181], v151 offset:2048
	ds_read_b128 v[182:185], v151 offset:3072
	s_add_u32 s24, s22, 0xfffc0080
	s_addc_u32 s25, s23, -1
	s_cmp_eq_u32 s54, 12
	s_cselect_b32 s27, s15, s25
	s_cselect_b32 s26, s50, s24
	s_cselect_b32 s25, s13, s53
	s_cselect_b32 s24, s51, s52
	v_lshl_add_u64 v[218:219], s[22:23], 0, v[140:141]
	s_add_i32 m0, s37, 0xc000
	ds_read_b128 v[186:189], v152
	ds_read_b128 v[190:193], v152 offset:1024
	ds_read_b128 v[194:197], v152 offset:2048
	ds_read_b128 v[198:201], v152 offset:3072
	ds_read_b128 v[202:205], v152 offset:4096
	ds_read_b128 v[206:209], v152 offset:5120
	ds_read_b128 v[210:213], v152 offset:6144
	ds_read_b128 v[214:217], v152 offset:7168
	global_load_lds_dwordx4 v[218:219], off
	v_lshl_add_u64 v[218:219], s[22:23], 0, v[142:143]
	s_add_i32 m0, s37, 0xe000
	s_nop 0
	global_load_lds_dwordx4 v[218:219], off
	s_add_i32 s44, s44, 1
	s_mul_i32 s0, s44, s46
	s_mul_hi_u32 s1, s44, s33
	s_add_i32 s1, s1, s0
	s_mul_i32 s0, s44, s33
	s_add_u32 s16, s0, s87
	s_addc_u32 s17, s1, s35
	v_cmp_lt_i64_e64 s[0:1], s[16:17], v[144:145]
	s_ashr_i32 s12, s16, 31
	s_lshr_b32 s12, s12, 29
	s_add_i32 s12, s16, s12
	s_ashr_i32 s13, s12, 3
	s_and_b32 s12, s12, -8
	s_sub_i32 s12, s16, s12
	s_cmp_lt_i32 s12, 0
	s_cselect_b32 s14, s36, 0x160
	s_mul_i32 s12, s12, s14
	s_add_i32 s12, s12, s13
	s_mul_hi_i32 s13, s12, 0x2e8ba2e9
	s_lshr_b32 s14, s13, 31
	s_ashr_i32 s13, s13, 4
	s_add_i32 s13, s13, s14
	s_lshl_b32 s14, s13, 2
	s_mul_i32 s13, s13, 88
	s_sub_i32 s13, s12, s13
	s_lshr_b32 s12, s13, 2
	s_and_b32 s13, s13, 3
	s_add_i32 s14, s14, s13
	s_ashr_i32 s15, s14, 31
	s_lshl_b64 s[16:17], s[14:15], 19
	s_add_u32 s16, s28, s16
	s_addc_u32 s17, s29, s17
	s_and_b64 s[18:19], s[0:1], exec
	s_cselect_b32 s15, s17, s29
	s_cselect_b32 s50, s16, s28
	s_ashr_i32 s13, s12, 31
	s_lshl_b64 s[18:19], s[12:13], 19
	s_add_u32 s18, s30, s18
	s_addc_u32 s19, s31, s19
	s_and_b64 s[98:99], s[0:1], exec
	s_cselect_b32 s13, s19, s31
	s_cselect_b32 s51, s18, s30
	s_waitcnt vmcnt(8)
	s_waitcnt lgkmcnt(0)
	s_barrier
	s_setprio 1
	s_waitcnt lgkmcnt(0)
	v_mfma_f32_16x16x32_bf16 v[126:129], v[154:157], v[186:189], 0
	v_mfma_f32_16x16x32_bf16 v[122:125], v[162:165], v[186:189], 0
	v_mfma_f32_16x16x32_bf16 v[110:113], v[154:157], v[194:197], 0
	v_mfma_f32_16x16x32_bf16 v[106:109], v[162:165], v[194:197], 0
	v_mfma_f32_16x16x32_bf16 v[94:97], v[154:157], v[202:205], 0
	v_mfma_f32_16x16x32_bf16 v[90:93], v[162:165], v[202:205], 0
	v_mfma_f32_16x16x32_bf16 v[78:81], v[154:157], v[210:213], 0
	v_mfma_f32_16x16x32_bf16 v[74:77], v[162:165], v[210:213], 0
	v_mfma_f32_16x16x32_bf16 v[126:129], v[158:161], v[190:193], v[126:129]
	v_mfma_f32_16x16x32_bf16 v[122:125], v[166:169], v[190:193], v[122:125]
	v_mfma_f32_16x16x32_bf16 v[110:113], v[158:161], v[198:201], v[110:113]
	v_mfma_f32_16x16x32_bf16 v[106:109], v[166:169], v[198:201], v[106:109]
	v_mfma_f32_16x16x32_bf16 v[94:97], v[158:161], v[206:209], v[94:97]
	v_mfma_f32_16x16x32_bf16 v[90:93], v[166:169], v[206:209], v[90:93]
	v_mfma_f32_16x16x32_bf16 v[78:81], v[158:161], v[214:217], v[78:81]
	v_mfma_f32_16x16x32_bf16 v[74:77], v[166:169], v[214:217], v[74:77]
	s_setprio 0
	s_setprio 1
	v_mfma_f32_16x16x32_bf16 v[118:121], v[170:173], v[186:189], 0
	v_mfma_f32_16x16x32_bf16 v[114:117], v[178:181], v[186:189], 0
	v_mfma_f32_16x16x32_bf16 v[102:105], v[170:173], v[194:197], 0
	v_mfma_f32_16x16x32_bf16 v[98:101], v[178:181], v[194:197], 0
	v_mfma_f32_16x16x32_bf16 v[86:89], v[170:173], v[202:205], 0
	v_mfma_f32_16x16x32_bf16 v[82:85], v[178:181], v[202:205], 0
	v_mfma_f32_16x16x32_bf16 v[70:73], v[170:173], v[210:213], 0
	v_mfma_f32_16x16x32_bf16 v[66:69], v[178:181], v[210:213], 0
	v_mfma_f32_16x16x32_bf16 v[118:121], v[174:177], v[190:193], v[118:121]
	v_mfma_f32_16x16x32_bf16 v[114:117], v[182:185], v[190:193], v[114:117]
	v_mfma_f32_16x16x32_bf16 v[102:105], v[174:177], v[198:201], v[102:105]
	v_mfma_f32_16x16x32_bf16 v[98:101], v[182:185], v[198:201], v[98:101]
	v_mfma_f32_16x16x32_bf16 v[86:89], v[174:177], v[206:209], v[86:89]
	v_mfma_f32_16x16x32_bf16 v[82:85], v[182:185], v[206:209], v[82:85]
	v_mfma_f32_16x16x32_bf16 v[70:73], v[174:177], v[214:217], v[70:73]
	v_mfma_f32_16x16x32_bf16 v[66:69], v[182:185], v[214:217], v[66:69]
	s_setprio 0
	s_barrier
; #define PG8_STAGE(bufoff, gbase, voff) do { _Pragma("unroll") for (int _i = 0; _i < 2; ++_i) \
;         __builtin_amdgcn_global_load_lds((const unsigned*)((const char*)(gbase) + (voff)[_i]), (PG8_LAS unsigned*)(lds + (bufoff) + ldsw + _i * 8192), 16, 0, 0); } while (0)
; #define PG8_LDA(dst, b, h) do { _Pragma("unroll") for (int m = 0; m < 4; ++m) _Pragma("unroll") for (int k = 0; k < 2; ++k) dst[m][k] = *(const PG8_LAS bf16x8*)(lds + PG8_SA(b, h) + aoff + m * 2048 + k * 1024); } while (0)
; #define PG8_MMA(ai, bj, At, Bt) do { __builtin_amdgcn_s_setprio(1); _Pragma("unroll") for (int m = 0; m < 4; ++m) _Pragma("unroll") for (int n = 0; n < 2; ++n) _Pragma("unroll") for (int k = 0; k < 2; ++k) \
;         acc[ai][bj][m][n] = __builtin_amdgcn_mfma_f32_16x16x32_bf16(Bt[n][k], At[m][k], acc[ai][bj][m][n], 0, 0, 0); __builtin_amdgcn_s_setprio(0); } while (0)
; #define PG8_WAIT_V(n) asm volatile("s_waitcnt vmcnt(" #n ")" ::: "memory")
; #define PG8_WAIT_L(n) asm volatile("s_waitcnt lgkmcnt(" #n ")" ::: "memory")
; #define PG8_BAR __builtin_amdgcn_s_barrier()
; #define PG8_SCHED __builtin_amdgcn_sched_barrier(0)
; template <class Epi, class Sched, bool ALIGN_EPI = false, bool SP2 = false>
; __device__ __forceinline__ void gemm_phase(PG8_LAS unsigned char* lds, const Gemm g, const Sched& S, const Epi& E) {
;     ...
;             PG8_LDA(At, 0, 1); PG8_STAGE(PG8_SB(0, 0), b2, voffB); PG8_STAGE(PG8_SB(0, 1), b2 + hstep, voffB); PG8_STAGE(PG8_SA(0, 0), a2, voffA);
;             PG8_WAIT_V(8); PG8_WAIT_L(0); PG8_BAR; PG8_MMA(1, 0, At, B0); PG8_MMA(1, 1, At, B1); PG8_BAR; PG8_SCHED;
	s_add_i32 s55, s47, s34
	v_lshl_add_u64 v[218:219], s[24:25], 0, v[134:135]
	s_mov_b32 m0, s55
	ds_read_b128 v[186:189], v152 offset:16384
	ds_read_b128 v[190:193], v152 offset:17408
	ds_read_b128 v[194:197], v152 offset:18432
	ds_read_b128 v[198:201], v152 offset:19456
	ds_read_b128 v[202:205], v152 offset:20480
	ds_read_b128 v[206:209], v152 offset:21504
	ds_read_b128 v[210:213], v152 offset:22528
	ds_read_b128 v[214:217], v152 offset:23552
	global_load_lds_dwordx4 v[218:219], off
	s_add_i32 m0, s55, 0x2000
	s_add_u32 s56, s24, 0x40000
	v_lshl_add_u64 v[222:223], s[24:25], 0, v[130:131]
	s_addc_u32 s57, s25, 0
	s_add_i32 s55, s48, s34
	global_load_lds_dwordx4 v[222:223], off
	v_lshl_add_u64 v[224:225], s[56:57], 0, v[134:135]
	s_mov_b32 m0, s55
	v_lshl_add_u64 v[226:227], s[26:27], 0, v[132:133]
	global_load_lds_dwordx4 v[224:225], off
	v_lshl_add_u64 v[224:225], s[56:57], 0, v[130:131]
	s_add_i32 m0, s55, 0x2000
	s_nop 0
	global_load_lds_dwordx4 v[224:225], off
	v_lshl_add_u64 v[224:225], s[26:27], 0, v[136:137]
	s_mov_b32 m0, s37
	s_nop 0
	global_load_lds_dwordx4 v[224:225], off
	s_mov_b32 m0, s38
	s_nop 0
	global_load_lds_dwordx4 v[226:227], off
	s_waitcnt vmcnt(8)
	s_waitcnt lgkmcnt(0)
	s_barrier
	s_setprio 1
	s_waitcnt lgkmcnt(0)
	v_mfma_f32_16x16x32_bf16 v[62:65], v[154:157], v[186:189], 0
	v_mfma_f32_16x16x32_bf16 v[58:61], v[162:165], v[186:189], 0
	v_mfma_f32_16x16x32_bf16 v[46:49], v[154:157], v[194:197], 0
	v_mfma_f32_16x16x32_bf16 v[42:45], v[162:165], v[194:197], 0
	v_mfma_f32_16x16x32_bf16 v[30:33], v[154:157], v[202:205], 0
	v_mfma_f32_16x16x32_bf16 v[26:29], v[162:165], v[202:205], 0
	v_mfma_f32_16x16x32_bf16 v[14:17], v[154:157], v[210:213], 0
	v_mfma_f32_16x16x32_bf16 v[10:13], v[162:165], v[210:213], 0
	v_mfma_f32_16x16x32_bf16 v[62:65], v[158:161], v[190:193], v[62:65]
	v_mfma_f32_16x16x32_bf16 v[58:61], v[166:169], v[190:193], v[58:61]
	v_mfma_f32_16x16x32_bf16 v[46:49], v[158:161], v[198:201], v[46:49]
	v_mfma_f32_16x16x32_bf16 v[42:45], v[166:169], v[198:201], v[42:45]
	v_mfma_f32_16x16x32_bf16 v[30:33], v[158:161], v[206:209], v[30:33]
	v_mfma_f32_16x16x32_bf16 v[26:29], v[166:169], v[206:209], v[26:29]
	v_mfma_f32_16x16x32_bf16 v[14:17], v[158:161], v[214:217], v[14:17]
	v_mfma_f32_16x16x32_bf16 v[10:13], v[166:169], v[214:217], v[10:13]
	s_setprio 0
	s_setprio 1
	v_mfma_f32_16x16x32_bf16 v[54:57], v[170:173], v[186:189], 0
	v_mfma_f32_16x16x32_bf16 v[50:53], v[178:181], v[186:189], 0
	v_mfma_f32_16x16x32_bf16 v[38:41], v[170:173], v[194:197], 0
	v_mfma_f32_16x16x32_bf16 v[34:37], v[178:181], v[194:197], 0
	v_mfma_f32_16x16x32_bf16 v[22:25], v[170:173], v[202:205], 0
	v_mfma_f32_16x16x32_bf16 v[18:21], v[178:181], v[202:205], 0
	v_mfma_f32_16x16x32_bf16 v[6:9], v[170:173], v[210:213], 0
	v_mfma_f32_16x16x32_bf16 v[2:5], v[178:181], v[210:213], 0
	v_mfma_f32_16x16x32_bf16 v[54:57], v[174:177], v[190:193], v[54:57]
	v_mfma_f32_16x16x32_bf16 v[50:53], v[182:185], v[190:193], v[50:53]
	v_mfma_f32_16x16x32_bf16 v[38:41], v[174:177], v[198:201], v[38:41]
	v_mfma_f32_16x16x32_bf16 v[34:37], v[182:185], v[198:201], v[34:37]
	v_mfma_f32_16x16x32_bf16 v[22:25], v[174:177], v[206:209], v[22:25]
	v_mfma_f32_16x16x32_bf16 v[18:21], v[182:185], v[206:209], v[18:21]
	v_mfma_f32_16x16x32_bf16 v[6:9], v[174:177], v[214:217], v[6:9]
	v_mfma_f32_16x16x32_bf16 v[2:5], v[182:185], v[214:217], v[2:5]
	s_setprio 0
	s_barrier
	s_branch .Lpz1_mid

;     __host__ __device__ bool next(int i, Unit& u) const { if (!b.next(i >> 1, u)) return false; u.sel = i & 1; return true; }
;     __host__ __device__ bool next(int i, Unit& u) const {
;         const long L = (long)i * G + c; if (L >= nwg) return false;
;         int wgid = (int)L; { const int q = nwg / NXCD, r = nwg % NXCD, xcd = wgid % NXCD, off = wgid / NXCD; wgid = (xcd < r ? xcd * (q + 1) : r * (q + 1) + (xcd - r) * q) + off; }
;         const int nig = WGM * nN, gid = wgid / nig, fm = gid * WGM, gsz = (nM - fm) < WGM ? (nM - fm) : WGM;
;         u.pm = fm + ((wgid % nig) % gsz); u.pn = (wgid % nig) / gsz; u.sel = 0; return true;
.LBB0_426:
	s_cmp_lt_i32 s48, 5
	s_cselect_b64 s[2:3], -1, 0
	s_and_b64 s[0:1], s[2:3], s[0:1]
	s_andn2_b64 vcc, exec, s[0:1]
	v_writelane_b32 v254, s87, 12
	s_cbranch_vccnz .LBB0_578
	s_cmpk_lt_i32 s87, 0xd00
	v_readfirstlane_b32 s8, v0
	s_mov_b32 s63, 0
	s_cselect_b64 s[2:3], -1, 0
	s_cmpk_gt_i32 s87, 0xcff
	s_cbranch_scc1 .LBB0_429
	s_waitcnt lgkmcnt(0)
	s_ashr_i32 s4, s87, 31
	s_lshr_b32 s4, s4, 29
	s_add_i32 s4, s87, s4
	s_ashr_i32 s5, s4, 3
	s_and_b32 s4, s4, -8
	s_sub_i32 s4, s87, s4
	s_cmp_lt_i32 s4, 0
	s_movk_i32 s6, 0x1a1
	s_cselect_b32 s6, s6, 0x1a0
	s_mul_i32 s4, s4, s6
	s_add_i32 s4, s4, s5
	s_mul_hi_i32 s5, s4, 0x4ec4ec4f
	s_lshr_b32 s6, s5, 31
	s_ashr_i32 s5, s5, 5
	s_add_i32 s5, s5, s6
	s_lshl_b32 s6, s5, 2
	s_mul_i32 s5, s5, 104
	s_sub_i32 s4, s4, s5
	s_lshr_b32 s7, s4, 2
	s_and_b32 s4, s4, 3
	s_add_i32 s4, s6, s4
	s_mov_b32 s6, s7

;     __host__ __device__ bool next(int i, Unit& u) const { if (!b.next(i >> 1, u)) return false; u.sel = i & 1; return true; }
; #define PG8_STAGE(bufoff, gbase, voff) do { _Pragma("unroll") for (int _i = 0; _i < 2; ++_i) \
;         __builtin_amdgcn_global_load_lds((const unsigned*)((const char*)(gbase) + (voff)[_i]), (PG8_LAS unsigned*)(lds + (bufoff) + ldsw + _i * 8192), 16, 0, 0); } while (0)
; #define PG8_LDA(dst, b, h) do { _Pragma("unroll") for (int m = 0; m < 4; ++m) _Pragma("unroll") for (int k = 0; k < 2; ++k) dst[m][k] = *(const PG8_LAS bf16x8*)(lds + PG8_SA(b, h) + aoff + m * 2048 + k * 1024); } while (0)
; #define PG8_WAIT_V(n) asm volatile("s_waitcnt vmcnt(" #n ")" ::: "memory")
;     __host__ __device__ bool next(int i, Unit& u) const {
;         const long L = (long)i * G + c; if (L >= nwg) return false;
;         int wgid = (int)L; { const int q = nwg / NXCD, r = nwg % NXCD, xcd = wgid % NXCD, off = wgid / NXCD; wgid = (xcd < r ? xcd * (q + 1) : r * (q + 1) + (xcd - r) * q) + off; }
;         const int nig = WGM * nN, gid = wgid / nig, fm = gid * WGM, gsz = (nM - fm) < WGM ? (nM - fm) : WGM;
;         u.pm = fm + ((wgid % nig) % gsz); u.pn = (wgid % nig) / gsz; u.sel = 0; return true;
; template <class Epi, class Sched, bool ALIGN_EPI = false, bool SP2 = false>
; __device__ __forceinline__ void gemm_phase(PG8_LAS unsigned char* lds, const Gemm g, const Sched& S, const Epi& E) {
;     ...
;         const bool has_next = S.next(ui + 1, nxt);
;         const char* nA = has_next ? PG8_ABASE(nxt) : cA; const char* nB = has_next ? PG8_BBASE(nxt) : cB;
;         for (int t = 0; t < nt; t += 2) {
;             const bool last = (t == nt - 2);
;             const char* a1 = cA + (size_t)(t + 1) * kstepA;
;             const char* a2 = last ? nA : cA + (size_t)(t + 2) * kstepA; const char* b2 = last ? nB : cB + (size_t)(t + 2) * kstep;
;             const char* a3 = a2 + kstepA; const char* b3 = b2 + kstep;
;             if (last && has_next) S.a_ready(nxt);
;             if constexpr (SP2) {
;             PG8_LDB(B0, 0, 0); PG8_LDB(B1, 0, 1); PG8_SCHED; PG8_LDA(At, 0, 0); PG8_STAGE(PG8_SA(1, 1), a1 + hstep, voffA);
;             PG8_WAIT_V(8); PG8_WAIT_L(0); PG8_BAR; PG8_MMA(0, 0, At, B0); PG8_MMA(0, 1, At, B1); PG8_BAR; PG8_SCHED;
;             if constexpr (Epi::PREFETCH) { if (t == tpf) E.prefetch(cur, wid, lane); }
.LBB0_435:
	s_ashr_i32 s5, s4, 31
	s_lshl_b32 s8, s6, 8
	s_lshl_b64 s[28:29], s[4:5], 14
	s_ashr_i32 s5, s4, 5
	s_ashr_i32 s9, s8, 31
	s_add_u32 s52, s14, s28
	s_mul_hi_i32 s54, s5, 0x6800
	s_mulk_i32 s5, 0x6800
	s_addc_u32 s53, s88, s29
	s_add_u32 s5, s77, s5
	s_addc_u32 s55, s78, s54
	s_lshl_b64 s[28:29], s[8:9], 2
	s_add_u32 s54, s5, s28
	s_addc_u32 s55, s55, s29
	s_add_u32 s5, s56, 0x100
	v_lshl_add_u64 v[196:197], s[10:11], 0, v[188:189]
	v_lshl_add_u64 v[198:199], s[10:11], 0, v[190:191]
	s_addc_u32 s9, s57, 0
	s_mov_b32 s28, 0
	s_mov_b64 s[56:57], 0
	ds_read_b128 v[162:165], v208
	ds_read_b128 v[166:169], v208 offset:1024
	ds_read_b128 v[170:173], v208 offset:2048
	ds_read_b128 v[174:177], v208 offset:3072
	ds_read_b128 v[146:149], v209
	ds_read_b128 v[150:153], v209 offset:1024
	ds_read_b128 v[154:157], v209 offset:2048
	ds_read_b128 v[158:161], v209 offset:3072
	v_lshl_add_u64 v[42:43], v[196:197], 0, s[56:57]
	s_add_i32 m0, s69, 0xc000
	ds_read_b128 v[212:215], v210
	ds_read_b128 v[216:219], v210 offset:1024
	ds_read_b128 v[222:225], v210 offset:2048
	ds_read_b128 v[226:229], v210 offset:3072
	ds_read_b128 v[230:233], v210 offset:4096
	ds_read_b128 v[234:237], v210 offset:5120
	ds_read_b128 v[238:241], v210 offset:6144
	ds_read_b128 v[242:245], v210 offset:7168
	global_load_lds_dwordx4 v[42:43], off
	v_lshl_add_u64 v[42:43], v[198:199], 0, s[56:57]
	s_add_i32 m0, s69, 0xe000
	s_nop 0
	global_load_lds_dwordx4 v[42:43], off
	s_add_i32 s15, s15, 1
	s_mul_i32 s2, s15, s86
	s_mul_hi_u32 s3, s15, s33
	s_add_i32 s3, s3, s2
	s_mul_i32 s2, s15, s33
	v_readlane_b32 s98, v254, 12
	s_add_u32 s100, s2, s98
	s_addc_u32 s101, s3, s87
	v_cmp_lt_i64_e64 s[2:3], s[100:101], v[192:193]
	s_ashr_i32 s98, s100, 31
	s_lshr_b32 s98, s98, 29
	s_add_i32 s98, s100, s98
	s_ashr_i32 s7, s98, 3
	s_and_b32 s98, s98, -8
	s_sub_i32 s98, s100, s98
	s_cmp_lt_i32 s98, 0
	s_movk_i32 s100, 0x1a1
	s_cselect_b32 s100, s100, 0x1a0
	s_mul_i32 s98, s98, s100
	s_add_i32 s98, s98, s7
	s_mul_hi_i32 s7, s98, 0x4ec4ec4f
	s_lshr_b32 s100, s7, 31
	s_ashr_i32 s7, s7, 5
	s_add_i32 s7, s7, s100
	s_lshl_b32 s100, s7, 2
	s_mul_i32 s7, s7, 104
	s_sub_i32 s98, s98, s7
	s_lshr_b32 s44, s98, 2
	s_and_b32 s98, s98, 3
	s_add_i32 s46, s100, s98
	s_ashr_i32 s47, s46, 31
	s_lshl_b64 s[100:101], s[46:47], 19
	s_add_u32 s48, s64, s100
	s_addc_u32 s49, s65, s101
	s_and_b64 s[100:101], s[2:3], exec
	s_cselect_b32 s7, s49, s65
	s_cselect_b32 s31, s48, s64
	s_ashr_i32 s45, s44, 31
	s_lshl_b64 s[100:101], s[44:45], 19
	s_add_u32 s50, s66, s100
	s_addc_u32 s51, s67, s101
	s_and_b64 s[100:101], s[2:3], exec
	s_cselect_b32 s45, s51, s67
	s_cselect_b32 s47, s50, s66
	s_waitcnt vmcnt(8)
	s_waitcnt lgkmcnt(0)
	s_barrier
	s_setprio 1
	s_waitcnt lgkmcnt(0)
	v_mfma_f32_16x16x32_bf16 v[42:45], v[162:165], v[212:215], 0
	v_mfma_f32_16x16x32_bf16 v[46:49], v[170:173], v[212:215], 0
	v_mfma_f32_16x16x32_bf16 v[50:53], v[162:165], v[222:225], 0
	v_mfma_f32_16x16x32_bf16 v[54:57], v[170:173], v[222:225], 0
	v_mfma_f32_16x16x32_bf16 v[110:113], v[162:165], v[230:233], 0
	v_mfma_f32_16x16x32_bf16 v[106:109], v[170:173], v[230:233], 0
	v_mfma_f32_16x16x32_bf16 v[94:97], v[162:165], v[238:241], 0
	v_mfma_f32_16x16x32_bf16 v[90:93], v[170:173], v[238:241], 0
	v_mfma_f32_16x16x32_bf16 v[42:45], v[166:169], v[216:219], v[42:45]
	v_mfma_f32_16x16x32_bf16 v[46:49], v[174:177], v[216:219], v[46:49]
	v_mfma_f32_16x16x32_bf16 v[50:53], v[166:169], v[226:229], v[50:53]
	v_mfma_f32_16x16x32_bf16 v[54:57], v[174:177], v[226:229], v[54:57]
	v_mfma_f32_16x16x32_bf16 v[110:113], v[166:169], v[234:237], v[110:113]
	v_mfma_f32_16x16x32_bf16 v[106:109], v[174:177], v[234:237], v[106:109]
	v_mfma_f32_16x16x32_bf16 v[94:97], v[166:169], v[242:245], v[94:97]
	v_mfma_f32_16x16x32_bf16 v[90:93], v[174:177], v[242:245], v[90:93]
	s_setprio 0
	s_setprio 1
	v_mfma_f32_16x16x32_bf16 v[122:125], v[146:149], v[212:215], 0
	v_mfma_f32_16x16x32_bf16 v[134:137], v[150:153], v[216:219], v[122:125]
	v_mfma_f32_16x16x32_bf16 v[122:125], v[154:157], v[212:215], 0
	v_mfma_f32_16x16x32_bf16 v[118:121], v[146:149], v[222:225], 0
	v_mfma_f32_16x16x32_bf16 v[114:117], v[154:157], v[222:225], 0
	v_mfma_f32_16x16x32_bf16 v[102:105], v[146:149], v[230:233], 0
	v_mfma_f32_16x16x32_bf16 v[98:101], v[154:157], v[230:233], 0
	v_mfma_f32_16x16x32_bf16 v[86:89], v[146:149], v[238:241], 0
	v_mfma_f32_16x16x32_bf16 v[82:85], v[154:157], v[238:241], 0
	v_mfma_f32_16x16x32_bf16 v[130:133], v[158:161], v[216:219], v[122:125]
	v_mfma_f32_16x16x32_bf16 v[118:121], v[150:153], v[226:229], v[118:121]
	v_mfma_f32_16x16x32_bf16 v[114:117], v[158:161], v[226:229], v[114:117]
	v_mfma_f32_16x16x32_bf16 v[102:105], v[150:153], v[234:237], v[102:105]
	v_mfma_f32_16x16x32_bf16 v[98:101], v[158:161], v[234:237], v[98:101]
	v_mfma_f32_16x16x32_bf16 v[86:89], v[150:153], v[242:245], v[86:89]
	v_mfma_f32_16x16x32_bf16 v[82:85], v[158:161], v[242:245], v[82:85]
	s_setprio 0
	s_barrier
	s_cmp_lg_u32 s63, s28
	s_cbranch_scc1 .Lpz3_a
	v_mov_b32_e32 v186, v207
	s_add_i32 m0, s62, 0x20000
	v_lshl_add_u64 v[122:123], s[52:53], 0, v[186:187]
	s_mov_b64 s[58:59], 0x400
	global_load_lds_dwordx4 v186, s[52:53]
	v_lshl_add_u64 v[122:123], v[122:123], 0, s[58:59]
	s_add_i32 m0, s62, 0x20400
	s_andn2_b64 vcc, exec, s[40:41]
	global_load_lds_dwordx4 v[122:123], off
	s_cbranch_vccnz .Lpz3_a
	v_lshl_add_u64 v[122:123], s[54:55], 0, v[186:187]
	s_mov_b32 m0, s30
	s_nop 0
	global_load_lds_dwordx4 v[122:123], off
	s_branch .Lpz3_a

;     __host__ __device__ bool next(int i, Unit& u) const { if (!b.next(i >> 1, u)) return false; u.sel = i & 1; return true; }
;     __host__ __device__ bool next(int i, Unit& u) const {
;         const long L = (long)i * G + c; if (L >= nwg) return false;
; template <class Epi, class Sched, bool ALIGN_EPI = false, bool SP2 = false>
; __device__ __forceinline__ void gemm_phase(PG8_LAS unsigned char* lds, const Gemm g, const Sched& S, const Epi& E) {
;     const int tid = threadIdx.x, wid = __builtin_amdgcn_readfirstlane(tid >> 6), lane = tid & 63, wr = wid >> 2, wc = wid & 3, fr = lane & 15, fq = lane >> 4;
;     const int K = g.K, nt = K / BK;
;     unsigned voffA[2], voffB[2];
; #pragma unroll
;     for (int i = 0; i < 2; ++i) { int R, C; stage_rc(tid * 16 + i * 8192, R, C); const int Rb = Epi::PERM ? ((R & ~31) + perm32(R & 31)) : R;
;         voffA[i] = Epi::AIL ? (unsigned)((R >> 1) * (2 * K) + (C >> 5) * 64 + (R & 1) * 32 + (C & 31)) * 2u : (unsigned)(R * K + C) * 2u; voffB[i] = (unsigned)(Rb * K + C) * 2u; }
;     const size_t kstep = (size_t)(BK * 2);
;     const size_t kstepA = Epi::AIL ? (size_t)(BK * 4) : kstep;
;     const size_t hstep = (size_t)HALF * K * 2;
;     const size_t tstep = 2 * hstep;
;     const unsigned ldsw = (unsigned)wid * 1024u;
;     const int aoff = lds_byte(wr * 64 + fr, fq * 8), boff = lds_byte(wc * 32 + fr, fq * 8);
;     ...
;     Unit cur, nxt; int ui = 0;
;     int tpf = 0; asm volatile("" : "+s"(tpf));
;     if (!S.next(0, cur)) return;
;     f32x4 acc[2][2][4][2];
; #pragma unroll
;     for (int a = 0; a < 2; ++a)
; #pragma unroll
;         for (int b = 0; b < 2; ++b)
; #pragma unroll
;             for (int m = 0; m < 4; ++m)
; #pragma unroll
;                 for (int n = 0; n < 2; ++n) acc[a][b][m][n] = (f32x4){0.f, 0.f, 0.f, 0.f};
;     bf16x8 At[4][2], B0[2][2], B1[2][2];
;     const char* cA = PG8_ABASE(cur); const char* cB = PG8_BBASE(cur);
;     S.a_ready(cur);
;     if constexpr (SP2) {
;         PG8_STAGE(PG8_SB(0, 0), cB, voffB); PG8_STAGE(PG8_SB(0, 1), cB + hstep, voffB); PG8_STAGE(PG8_SA(0, 0), cA, voffA); PG8_STAGE(PG8_SA(0, 1), cA + hstep, voffA);
;         if (wr == 1) PG8_BAR;
;         PG8_WAIT_V(2); PG8_BAR;
;         PG8_STAGE(PG8_SB(1, 0), cB + kstep, voffB); PG8_STAGE(PG8_SA(1, 0), cA + kstepA, voffA); PG8_STAGE(PG8_SB(1, 1), cB + hstep + kstep, voffB);
;         PG8_WAIT_V(6); PG8_BAR;
.LBB0_975:
	s_cmp_lt_i32 s48, 9
	s_cselect_b64 s[2:3], -1, 0
	s_and_b64 s[0:1], s[2:3], s[0:1]
	s_andn2_b64 vcc, exec, s[0:1]
	s_cbranch_vccnz .LBB0_995
	v_readfirstlane_b32 s3, v0
	s_mov_b32 s46, 0
	s_cmpk_gt_i32 s87, 0xaff
	s_cbranch_scc1 .LBB0_995
	v_lshrrev_b32_e32 v1, 5, v0
	s_waitcnt lgkmcnt(0)
	v_lshrrev_b32_e32 v3, 1, v0
	v_and_b32_e32 v1, 4, v1
	v_bfe_u32 v2, v0, 2, 2
	v_and_b32_e32 v3, 24, v3
	s_add_u32 s47, s78, 0x8000000
	v_or3_b32 v1, v1, v2, v3
	v_lshlrev_b32_e32 v2, 4, v0
	s_addc_u32 s48, s79, 0
	v_or_b32_e32 v10, 0x2000, v2
	s_add_u32 s49, s78, 0x2d00000
	v_lshrrev_b32_e32 v3, 7, v10
	s_movk_i32 s2, 0x60
	s_addc_u32 s50, s79, 0
	v_and_or_b32 v4, v3, s2, v1
	v_bfe_u32 v13, v0, 2, 4
	s_movk_i32 s2, 0x70
	s_ashr_i32 s52, s87, 31
	v_and_or_b32 v3, v3, s2, v13
	s_lshr_b32 s2, s52, 29
	s_add_i32 s2, s87, s2
	s_lshr_b32 s14, s3, 6
	s_ashr_i32 s4, s2, 3
	s_and_b32 s2, s2, -8
	s_lshr_b32 s18, s3, 8
	s_lshl_b32 s51, s14, 10
	s_sub_i32 s2, s87, s2
	s_cmp_lt_i32 s2, 0
	s_movk_i32 s53, 0x161
	s_cselect_b32 s5, s53, 0x160
	s_mul_i32 s2, s2, s5
	s_add_i32 s2, s2, s4
	s_mul_hi_i32 s4, s2, 0x2e8ba2e9
	s_lshr_b32 s5, s4, 31
	s_ashr_i32 s4, s4, 4
	s_add_i32 s4, s4, s5
	s_lshl_b32 s5, s4, 2
	s_mul_i32 s4, s4, 88
	s_sub_i32 s4, s2, s4
	s_lshr_b32 s2, s4, 2
	s_and_b32 s4, s4, 3
	s_add_i32 s28, s5, s4
	v_and_b32_e32 v5, 32, v0
	s_ashr_i32 s29, s28, 31
	s_bfe_i64 s[6:7], s[2:3], 0x100000
	v_bitop3_b32 v11, v2, v5, 48 bitop3:0x6c
	v_and_b32_e32 v12, 64, v0
	s_lshl_b64 s[4:5], s[28:29], 19
	s_lshl_b64 s[6:7], s[6:7], 19
	v_or_b32_e32 v2, v11, v12
	s_add_u32 s40, s49, s6
	v_lshl_or_b32 v172, v3, 11, v2
	v_lshrrev_b32_e32 v3, 3, v0
	s_addc_u32 s41, s50, s7
	s_add_i32 s54, s51, 0
	v_and_or_b32 v1, v3, 32, v1
	s_add_i32 s55, s54, 0x10000
	s_add_i32 s56, s54, 0x12000
	v_lshl_or_b32 v174, v1, 11, v2
	s_mov_b32 m0, s55
	s_add_u32 s6, s40, 0x40000
	v_lshl_or_b32 v170, v4, 11, v2
	global_load_lds_dwordx4 v174, s[40:41]
	s_mov_b32 m0, s56
	s_addc_u32 s7, s41, 0
	s_add_i32 s57, s54, 0x14000
	s_add_i32 s58, s54, 0x16000
	global_load_lds_dwordx4 v170, s[40:41]
	s_mov_b32 m0, s57
	s_add_u32 s30, s47, s4
	v_and_or_b32 v1, v3, 48, v13
	global_load_lds_dwordx4 v174, s[6:7]
	s_mov_b32 m0, s58
	s_addc_u32 s31, s48, s5
	s_add_i32 s59, s54, 0x2000
	v_lshl_or_b32 v176, v1, 11, v2
	global_load_lds_dwordx4 v170, s[6:7]
	s_mov_b32 m0, s54
	s_add_u32 s4, s30, 0x40000
	global_load_lds_dwordx4 v176, s[30:31]
	s_mov_b32 m0, s59
	s_addc_u32 s5, s31, 0
	s_add_i32 s60, s54, 0x4000
	global_load_lds_dwordx4 v172, s[30:31]
	s_mov_b32 m0, s60
	s_add_i32 s61, s54, 0x6000
	global_load_lds_dwordx4 v176, s[4:5]
	s_mov_b32 m0, s61
	v_mov_b32_e32 v179, 0
	global_load_lds_dwordx4 v172, s[4:5]
	v_mov_b32_e32 v175, v179
	v_mov_b32_e32 v171, v179
	v_mov_b32_e32 v177, v179
	v_mov_b32_e32 v173, v179
	s_cmp_eq_u32 s18, 1
	v_lshl_add_u64 v[8:9], s[40:41], 0, v[174:175]
	v_lshl_add_u64 v[6:7], s[40:41], 0, v[170:171]
	v_lshl_add_u64 v[2:3], s[30:31], 0, v[176:177]
	s_cselect_b64 s[4:5], -1, 0
	s_cmp_lg_u32 s18, 1
	v_lshl_add_u64 v[4:5], s[30:31], 0, v[172:173]
	s_cbranch_scc1 .LBB0_979
	s_barrier

;     __host__ __device__ bool next(int i, Unit& u) const { if (!b.next(i >> 1, u)) return false; u.sel = i & 1; return true; }
; #define PG8_STAGE(bufoff, gbase, voff) do { _Pragma("unroll") for (int _i = 0; _i < 2; ++_i) \
;         __builtin_amdgcn_global_load_lds((const unsigned*)((const char*)(gbase) + (voff)[_i]), (PG8_LAS unsigned*)(lds + (bufoff) + ldsw + _i * 8192), 16, 0, 0); } while (0)
; #define PG8_LDA(dst, b, h) do { _Pragma("unroll") for (int m = 0; m < 4; ++m) _Pragma("unroll") for (int k = 0; k < 2; ++k) dst[m][k] = *(const PG8_LAS bf16x8*)(lds + PG8_SA(b, h) + aoff + m * 2048 + k * 1024); } while (0)
; #define PG8_WAIT_V(n) asm volatile("s_waitcnt vmcnt(" #n ")" ::: "memory")
;     __host__ __device__ bool next(int i, Unit& u) const {
;         const long L = (long)i * G + c; if (L >= nwg) return false;
;         int wgid = (int)L; { const int q = nwg / NXCD, r = nwg % NXCD, xcd = wgid % NXCD, off = wgid / NXCD; wgid = (xcd < r ? xcd * (q + 1) : r * (q + 1) + (xcd - r) * q) + off; }
;         const int nig = WGM * nN, gid = wgid / nig, fm = gid * WGM, gsz = (nM - fm) < WGM ? (nM - fm) : WGM;
;         u.pm = fm + ((wgid % nig) % gsz); u.pn = (wgid % nig) / gsz; u.sel = 0; return true;
; template <class Epi, class Sched, bool ALIGN_EPI = false, bool SP2 = false>
; __device__ __forceinline__ void gemm_phase(PG8_LAS unsigned char* lds, const Gemm g, const Sched& S, const Epi& E) {
;     ...
;         const bool has_next = S.next(ui + 1, nxt);
;         const char* nA = has_next ? PG8_ABASE(nxt) : cA; const char* nB = has_next ? PG8_BBASE(nxt) : cB;
;         for (int t = 0; t < nt; t += 2) {
;             const bool last = (t == nt - 2);
;             const char* a1 = cA + (size_t)(t + 1) * kstepA;
;             const char* a2 = last ? nA : cA + (size_t)(t + 2) * kstepA; const char* b2 = last ? nB : cB + (size_t)(t + 2) * kstep;
;             const char* a3 = a2 + kstepA; const char* b3 = b2 + kstep;
;             if (last && has_next) S.a_ready(nxt);
;             if constexpr (SP2) {
;             PG8_LDB(B0, 0, 0); PG8_LDB(B1, 0, 1); PG8_SCHED; PG8_LDA(At, 0, 0); PG8_STAGE(PG8_SA(1, 1), a1 + hstep, voffA);
;             PG8_WAIT_V(8); PG8_WAIT_L(0); PG8_BAR; PG8_MMA(0, 0, At, B0); PG8_MMA(0, 1, At, B1); PG8_BAR; PG8_SCHED;
;             if constexpr (Epi::PREFETCH) { if (t == tpf) E.prefetch(cur, wid, lane); }
.LBB0_982:
	s_ashr_i32 s29, s28, 31
	s_lshl_b32 s34, s34, 8
	s_lshl_b64 s[36:37], s[28:29], 14
	s_ashr_i32 s29, s28, 5
	s_ashr_i32 s35, s34, 31
	s_add_u32 s36, s10, s36
	s_mul_hi_i32 s38, s29, 0x5800
	s_mulk_i32 s29, 0x5800
	s_addc_u32 s37, s69, s37
	s_add_u32 s29, s62, s29
	s_addc_u32 s42, s63, s38
	s_lshl_b64 s[38:39], s[34:35], 2
	s_add_u32 s38, s29, s38
	s_addc_u32 s39, s42, s39
	s_add_u32 s29, s40, 0x100
	v_lshl_add_u64 v[188:189], s[30:31], 0, v[180:181]
	v_lshl_add_u64 v[190:191], s[30:31], 0, v[182:183]
	s_addc_u32 s35, s41, 0
	s_mov_b32 s83, 0
	s_mov_b64 s[40:41], 0
	ds_read_b128 v[154:157], v195
	ds_read_b128 v[158:161], v195 offset:1024
	ds_read_b128 v[162:165], v195 offset:2048
	ds_read_b128 v[166:169], v195 offset:3072
	ds_read_b128 v[138:141], v196
	ds_read_b128 v[142:145], v196 offset:1024
	ds_read_b128 v[146:149], v196 offset:2048
	ds_read_b128 v[150:153], v196 offset:3072
	v_lshl_add_u64 v[98:99], v[188:189], 0, s[40:41]
	s_add_i32 m0, s54, 0xc000
	ds_read_b128 v[200:203], v197
	ds_read_b128 v[204:207], v197 offset:1024
	ds_read_b128 v[208:211], v197 offset:2048
	ds_read_b128 v[212:215], v197 offset:3072
	ds_read_b128 v[216:219], v197 offset:4096
	ds_read_b128 v[220:223], v197 offset:5120
	ds_read_b128 v[224:227], v197 offset:6144
	ds_read_b128 v[228:231], v197 offset:7168
	global_load_lds_dwordx4 v[98:99], off
	v_lshl_add_u64 v[98:99], v[190:191], 0, s[40:41]
	s_add_i32 m0, s54, 0xe000
	s_nop 0
	global_load_lds_dwordx4 v[98:99], off
	s_add_i32 s11, s11, 1
	s_mul_i32 s2, s11, s68
	s_mul_hi_u32 s3, s11, s33
	s_add_i32 s3, s3, s2
	s_mul_i32 s2, s11, s33
	s_add_u32 s24, s2, s87
	s_addc_u32 s25, s3, s52
	v_cmp_lt_i64_e64 s[2:3], s[24:25], v[184:185]
	s_ashr_i32 s20, s24, 31
	s_lshr_b32 s20, s20, 29
	s_add_i32 s20, s24, s20
	s_ashr_i32 s21, s20, 3
	s_and_b32 s20, s20, -8
	s_sub_i32 s20, s24, s20
	s_cmp_lt_i32 s20, 0
	s_cselect_b32 s22, s53, 0x160
	s_mul_i32 s20, s20, s22
	s_add_i32 s20, s20, s21
	s_mul_hi_i32 s21, s20, 0x2e8ba2e9
	s_lshr_b32 s22, s21, 31
	s_ashr_i32 s21, s21, 4
	s_add_i32 s21, s21, s22
	s_lshl_b32 s22, s21, 2
	s_mul_i32 s21, s21, 88
	s_sub_i32 s21, s20, s21
	s_lshr_b32 s20, s21, 2
	s_and_b32 s21, s21, 3
	s_add_i32 s22, s22, s21
	s_ashr_i32 s23, s22, 31
	s_lshl_b64 s[24:25], s[22:23], 19
	s_add_u32 s24, s47, s24
	s_addc_u32 s25, s48, s25
	s_and_b64 s[26:27], s[2:3], exec
	s_cselect_b32 s23, s25, s48
	s_cselect_b32 s81, s24, s47
	s_ashr_i32 s21, s20, 31
	s_lshl_b64 s[26:27], s[20:21], 19
	s_add_u32 s26, s49, s26
	s_addc_u32 s27, s50, s27
	s_and_b64 s[98:99], s[2:3], exec
	s_cselect_b32 s21, s27, s50
	s_cselect_b32 s82, s26, s49
	s_waitcnt vmcnt(8)
	s_waitcnt lgkmcnt(0)
	s_barrier
	s_setprio 1
	s_waitcnt lgkmcnt(0)
	v_mfma_f32_16x16x32_bf16 v[98:101], v[154:157], v[200:203], 0
	v_mfma_f32_16x16x32_bf16 v[106:109], v[162:165], v[200:203], 0
	v_mfma_f32_16x16x32_bf16 v[118:121], v[154:157], v[208:211], 0
	v_mfma_f32_16x16x32_bf16 v[114:117], v[162:165], v[208:211], 0
	v_mfma_f32_16x16x32_bf16 v[94:97], v[154:157], v[216:219], 0
	v_mfma_f32_16x16x32_bf16 v[90:93], v[162:165], v[216:219], 0
	v_mfma_f32_16x16x32_bf16 v[78:81], v[154:157], v[224:227], 0
	v_mfma_f32_16x16x32_bf16 v[74:77], v[162:165], v[224:227], 0
	v_mfma_f32_16x16x32_bf16 v[98:101], v[158:161], v[204:207], v[98:101]
	v_mfma_f32_16x16x32_bf16 v[106:109], v[166:169], v[204:207], v[106:109]
	v_mfma_f32_16x16x32_bf16 v[118:121], v[158:161], v[212:215], v[118:121]
	v_mfma_f32_16x16x32_bf16 v[114:117], v[166:169], v[212:215], v[114:117]
	v_mfma_f32_16x16x32_bf16 v[94:97], v[158:161], v[220:223], v[94:97]
	v_mfma_f32_16x16x32_bf16 v[90:93], v[166:169], v[220:223], v[90:93]
	v_mfma_f32_16x16x32_bf16 v[78:81], v[158:161], v[228:231], v[78:81]
	v_mfma_f32_16x16x32_bf16 v[74:77], v[166:169], v[228:231], v[74:77]
	s_setprio 0
	s_setprio 1
	v_mfma_f32_16x16x32_bf16 v[126:129], v[138:141], v[200:203], 0
	v_mfma_f32_16x16x32_bf16 v[122:125], v[146:149], v[200:203], 0
	v_mfma_f32_16x16x32_bf16 v[110:113], v[138:141], v[208:211], 0
	v_mfma_f32_16x16x32_bf16 v[102:105], v[146:149], v[208:211], 0
	v_mfma_f32_16x16x32_bf16 v[86:89], v[138:141], v[216:219], 0
	v_mfma_f32_16x16x32_bf16 v[82:85], v[146:149], v[216:219], 0
	v_mfma_f32_16x16x32_bf16 v[70:73], v[138:141], v[224:227], 0
	v_mfma_f32_16x16x32_bf16 v[66:69], v[146:149], v[224:227], 0
	v_mfma_f32_16x16x32_bf16 v[126:129], v[142:145], v[204:207], v[126:129]
	v_mfma_f32_16x16x32_bf16 v[122:125], v[150:153], v[204:207], v[122:125]
	v_mfma_f32_16x16x32_bf16 v[110:113], v[142:145], v[212:215], v[110:113]
	v_mfma_f32_16x16x32_bf16 v[102:105], v[150:153], v[212:215], v[102:105]
	v_mfma_f32_16x16x32_bf16 v[86:89], v[142:145], v[220:223], v[86:89]
	v_mfma_f32_16x16x32_bf16 v[82:85], v[150:153], v[220:223], v[82:85]
	v_mfma_f32_16x16x32_bf16 v[70:73], v[142:145], v[228:231], v[70:73]
	v_mfma_f32_16x16x32_bf16 v[66:69], v[150:153], v[228:231], v[66:69]
	s_setprio 0
	s_barrier
	s_cmp_lg_u32 s46, s83
	s_cbranch_scc1 .Lpz5_a
	v_mov_b32_e32 v178, v194
	s_add_i32 m0, s79, 0x20000
	v_lshl_add_u64 v[130:131], s[36:37], 0, v[178:179]
	global_load_lds_dwordx4 v178, s[36:37]
	v_lshl_add_u64 v[130:131], v[130:131], 0, s[18:19]
	s_add_i32 m0, s79, 0x20400
	s_andn2_b64 vcc, exec, s[14:15]
	global_load_lds_dwordx4 v[130:131], off
	s_cbranch_vccnz .Lpz5_a
	v_lshl_add_u64 v[130:131], s[38:39], 0, v[178:179]
	s_add_i32 m0, 0, 0x24000
	s_nop 0
	global_load_lds_dwordx4 v[130:131], off
	s_branch .Lpz5_a
